# hidden activations H stored block-major (1 KiB blocks holding the LDS image): P6 epilogue stores and the P7 A-operand LDS-DMA pieces are each one contiguous 1 KiB instead of 16 row segments of 64 B; P
# speedup vs baseline: 1.0234x; 1.0140x over previous
.LBB0_647:
	s_or_b64 exec, exec, s[0:1]
	s_add_u32 s3, s72, 0xa00000
	s_addc_u32 s26, s73, 0
	s_cmpk_lt_i32 s2, 0x400
	s_cselect_b64 s[0:1], -1, 0
	v_writelane_b32 v243, s0, 14
	s_ashr_i32 s27, s2, 31
	s_mul_i32 s29, s75, s74
	v_writelane_b32 v243, s1, 15
	s_lshr_b32 s0, s27, 29
	s_add_i32 s0, s2, s0
	s_ashr_i32 s4, s0, 3
	s_and_b32 s0, s0, -8
	s_sub_i32 s5, s2, s0
	s_lshl_b32 s6, s5, 7
	s_ashr_i32 s75, s74, 31
	s_add_u32 s50, s72, 0x200
	s_addc_u32 s51, s73, 0
	s_add_u32 s52, s72, 0x1000
	s_addc_u32 s53, s73, 0
	s_add_u32 s54, s72, 0x1100
	s_addc_u32 s55, s73, 0
	s_add_u32 s56, s72, 0x1200
	s_addc_u32 s57, s73, 0
	s_add_u32 s58, s72, 0x1300
	s_addc_u32 s59, s73, 0
	s_cmp_eq_u32 s33, 15
	s_cselect_b64 s[0:1], -1, 0
	v_writelane_b32 v243, s0, 16
	s_cmp_eq_u32 s33, 14
	v_lshl_add_u64 v[0:1], v[0:1], 2, s[72:73]
	v_writelane_b32 v243, s1, 17
	s_cselect_b64 s[0:1], -1, 0
	v_writelane_b32 v243, s0, 18
	s_cmp_eq_u32 s33, 13
	s_mul_i32 s8, s5, 0x81
	v_writelane_b32 v243, s1, 19
	s_cselect_b64 s[0:1], -1, 0
	v_writelane_b32 v243, s0, 20
	s_cmp_eq_u32 s33, 12
	s_mul_i32 s29, s29, s89
	v_writelane_b32 v243, s1, 21
	s_cselect_b64 s[0:1], -1, 0
	v_writelane_b32 v243, s0, 22
	s_cmp_eq_u32 s33, 11
	v_mov_b32_e32 v133, 0
	v_writelane_b32 v243, s1, 23
	s_cselect_b64 s[0:1], -1, 0
	v_writelane_b32 v243, s0, 24
	s_cmp_eq_u32 s33, 10
	v_mov_b32_e32 v148, 0x358637bd
	v_writelane_b32 v243, s1, 25
	s_cselect_b64 s[0:1], -1, 0
	v_writelane_b32 v243, s0, 26
	s_cmp_eq_u32 s33, 9
	v_mov_b32_e32 v149, 1
	v_writelane_b32 v243, s1, 27
	s_cselect_b64 s[0:1], -1, 0
	v_writelane_b32 v243, s0, 28
	s_cmp_eq_u32 s33, 8
	v_mov_b64_e32 v[134:135], 0x400
	v_writelane_b32 v243, s1, 29
	s_cselect_b64 s[0:1], -1, 0
	v_writelane_b32 v243, s0, 30
	s_cmp_eq_u32 s33, 7
	v_mov_b64_e32 v[136:137], 0x3ff
	v_writelane_b32 v243, s1, 31
	s_cselect_b64 s[0:1], -1, 0
	v_writelane_b32 v243, s0, 32
	s_cmp_eq_u32 s33, 6
	v_mov_b64_e32 v[138:139], 0x100
	v_writelane_b32 v243, s1, 33
	s_cselect_b64 s[0:1], -1, 0
	v_writelane_b32 v243, s0, 34
	s_cmp_eq_u32 s33, 5
	v_mov_b64_e32 v[140:141], 0xff
	v_writelane_b32 v243, s1, 35
	s_cselect_b64 s[0:1], -1, 0
	v_writelane_b32 v243, s0, 36
	s_cmp_eq_u32 s33, 4
	s_mov_b64 s[70:71], -1
	v_writelane_b32 v243, s1, 37
	s_cselect_b64 s[0:1], -1, 0
	v_writelane_b32 v243, s0, 38
	s_cmp_eq_u32 s33, 3
	s_nop 0
	v_writelane_b32 v243, s1, 39
	s_cselect_b64 s[0:1], -1, 0
	v_writelane_b32 v243, s0, 40
	s_cmp_eq_u32 s33, 2
	s_barrier
	v_writelane_b32 v243, s1, 41
	s_cselect_b64 s[0:1], -1, 0
	v_writelane_b32 v243, s0, 42
	s_cmp_eq_u32 s33, 1
	s_nop 0
	v_writelane_b32 v243, s1, 43
	s_cselect_b64 s[0:1], -1, 0
	v_writelane_b32 v243, s0, 44
	s_cmp_eq_u32 s33, 0
	s_nop 0
	v_writelane_b32 v243, s1, 45
	s_cselect_b64 s[0:1], -1, 0
	v_writelane_b32 v243, s0, 46
	s_nop 1
	v_writelane_b32 v243, s1, 47
	s_add_u32 s0, s72, 0x3400
	s_addc_u32 s1, s73, 0
	s_add_u32 s62, s72, 0x3500
	s_addc_u32 s63, s73, 0
	v_writelane_b32 v243, s0, 48
	s_add_u32 s33, s72, 0x1200000
	s_addc_u32 s28, s73, 0
	v_writelane_b32 v243, s1, 49
	s_lshl_b32 s7, s5, 5
	s_mov_b64 s[0:1], 0x1400
	s_cmp_lt_i32 s5, 0
	v_lshl_add_u64 v[128:129], v[0:1], 0, s[0:1]
	s_mov_b64 s[0:1], 0x2400
	v_lshl_add_u64 v[130:131], v[0:1], 0, s[0:1]
	s_mul_i32 s5, s5, 33
	s_cselect_b32 s0, s8, s6
	s_cselect_b32 s5, s5, s7
	s_add_i32 s0, s0, s4
	s_ashr_i32 s1, s0, 31
	s_lshr_b32 s1, s1, 25
	s_add_i32 s1, s0, s1
	s_ashr_i32 s6, s1, 7
	s_and_b32 s1, s1, 0xff80
	s_sub_i32 s1, s0, s1
	s_bfe_i32 s0, s1, 0x80000
	s_bfe_u32 s0, s0, 0x3000c
	s_add_i32 s7, s1, s0
	s_bfe_i32 s0, s7, 0x80000
	s_and_b32 s7, s7, 0xf8
	s_sub_i32 s1, s1, s7
	s_lshl_b32 s6, s6, 3
	s_sext_i32_i8 s1, s1
	s_sext_i32_i16 s8, s0
	s_add_i32 s10, s6, s1
	s_lshr_b32 s0, s8, 3
	s_mov_b32 s6, s10
	s_ashr_i32 s11, s10, 31
	v_writelane_b32 v243, s6, 50
	s_bfe_i64 s[0:1], s[0:1], 0x100000
	s_ashr_i32 s91, s8, 3
	v_writelane_b32 v243, s7, 51
	s_lshl_b64 s[6:7], s[10:11], 19
	s_lshl_b64 s[0:1], s[0:1], 19
	s_add_u32 s68, s3, s0
	s_addc_u32 s69, s26, s1
	v_writelane_b32 v243, s6, 52
	s_add_u32 s0, s68, 0x40000
	s_addc_u32 s1, s69, 0
	v_writelane_b32 v243, s7, 53
	v_writelane_b32 v243, s0, 54
	s_nop 1
	v_writelane_b32 v243, s1, 55
	s_add_u32 s0, s68, 0x80
	s_addc_u32 s1, s69, 0
	v_writelane_b32 v243, s0, 56
	s_nop 1
	v_writelane_b32 v243, s1, 57
	s_add_u32 s0, s68, 0x40080
	s_addc_u32 s1, s69, 0
	v_writelane_b32 v243, s0, 58
	s_nop 1
	v_writelane_b32 v243, s1, 59
	s_add_i32 s0, s5, s4
	s_ashr_i32 s1, s0, 31
	s_lshr_b32 s1, s1, 27
	s_add_i32 s1, s0, s1
	s_ashr_i32 s4, s1, 5
	s_and_b32 s1, s1, 0xffe0
	s_sub_i32 s1, s0, s1
	s_bfe_i32 s0, s1, 0x80000
	s_bfe_u32 s0, s0, 0x3000c
	s_add_i32 s5, s1, s0
	s_bfe_i32 s0, s5, 0x80000
	s_and_b32 s5, s5, 0xf8
	s_sub_i32 s1, s1, s5
	s_lshl_b32 s4, s4, 3
	s_sext_i32_i16 s6, s0
	s_sext_i32_i8 s1, s1
	s_add_i32 s8, s4, s1
	s_ashr_i32 s1, s6, 3
	s_lshr_b32 s0, s6, 3
	v_writelane_b32 v243, s1, 60
	s_mov_b32 s4, s8
	s_ashr_i32 s9, s8, 31
	v_writelane_b32 v243, s4, 61
	s_bfe_i64 s[0:1], s[0:1], 0x100000
	s_lshl_b64 s[0:1], s[0:1], 21
	v_writelane_b32 v243, s5, 62
	s_lshl_b64 s[4:5], s[8:9], 21
	s_add_u32 s84, s33, s0
	s_addc_u32 s85, s28, s1
	s_add_u32 s0, s84, 0x100000
	s_addc_u32 s1, s85, 0
	s_add_u32 s88, s48, s4
	v_writelane_b32 v243, s0, 63
	s_addc_u32 s89, s49, s5
	s_nop 0
	v_writelane_b32 v242, s1, 0
	s_add_u32 s0, s88, 0x100000
	s_addc_u32 s1, s89, 0
	s_add_u32 s92, s84, 0x80
	s_addc_u32 s93, s85, 0
	s_add_u32 s94, s88, 0x800
	s_addc_u32 s95, s89, 0
	v_writelane_b32 v242, s0, 1
	s_add_u32 s96, s84, 0x100080
	s_addc_u32 s97, s85, 0
	v_writelane_b32 v242, s1, 2
	s_add_i32 s0, 0, 0x23fc0
	v_writelane_b32 v243, s0, 8
	s_add_i32 s0, 0, 0x23fc4
	v_writelane_b32 v242, s0, 3
	s_mov_b64 s[0:1], 0
	s_branch .LBB0_651

.LBB0_667:
	v_lshl_add_u32 v222, s77, 8, v154
	v_lshlrev_b32_e32 v223, 2, v222
	s_lshl_b32 s14, s77, 21
	s_lshl_b32 s15, s76, 13
	s_add_i32 s14, s14, s15
	v_and_b32_e32 v224, 15, v165
	v_lshlrev_b32_e32 v224, 6, v224
	v_and_b32_e32 v225, 0x30, v165
	v_or_b32_e32 v224, v224, v225
	v_and_b32_e32 v225, 8, v165
	v_lshlrev_b32_e32 v225, 2, v225
	v_xor_b32_e32 v224, v224, v225
	v_and_b32_e32 v225, 0xc0, v165
	v_lshl_or_b32 v224, v225, 4, v224
	v_and_b32_e32 v225, 0x100, v165
	v_lshl_or_b32 v224, v225, 11, v224
	v_add_u32_e32 v224, s14, v224
	v_add_u32_e32 v226, 0x1000, v224
	global_load_dword v166, v223, s[6:7]
	global_load_dword v168, v223, s[6:7] offset:64
	global_load_dword v170, v223, s[6:7] offset:128
	global_load_dword v172, v223, s[6:7] offset:192
	global_load_dword v174, v223, s[6:7] offset:512
	global_load_dword v176, v223, s[6:7] offset:576
	global_load_dword v178, v223, s[6:7] offset:640
	global_load_dword v180, v223, s[6:7] offset:704
	s_waitcnt vmcnt(7)
	v_fmamk_f32 v166, v166, 0x3a800000, v148
	v_rsq_f32_e32 v166, v166
	s_nop 0
	v_pk_mul_f32 v[124:125], v[124:125], v[166:167] op_sel_hi:[1,0]
	v_pk_mul_f32 v[126:127], v[126:127], v[166:167] op_sel_hi:[1,0]
	v_pk_mul_f32 v[120:121], v[120:121], v[166:167] op_sel_hi:[1,0]
	v_pk_mul_f32 v[122:123], v[122:123], v[166:167] op_sel_hi:[1,0]
	v_pk_mul_f32 v[116:117], v[116:117], v[166:167] op_sel_hi:[1,0]
	v_pk_mul_f32 v[118:119], v[118:119], v[166:167] op_sel_hi:[1,0]
	v_pk_mul_f32 v[112:113], v[112:113], v[166:167] op_sel_hi:[1,0]
	v_pk_mul_f32 v[114:115], v[114:115], v[166:167] op_sel_hi:[1,0]
	v_max_f32_e32 v124, 0, v124
	v_max_f32_e32 v125, 0, v125
	v_max_f32_e32 v126, 0, v126
	v_max_f32_e32 v127, 0, v127
	v_max_f32_e32 v120, 0, v120
	v_max_f32_e32 v121, 0, v121
	v_max_f32_e32 v122, 0, v122
	v_max_f32_e32 v123, 0, v123
	v_max_f32_e32 v116, 0, v116
	v_max_f32_e32 v117, 0, v117
	v_max_f32_e32 v118, 0, v118
	v_max_f32_e32 v119, 0, v119
	v_max_f32_e32 v112, 0, v112
	v_max_f32_e32 v113, 0, v113
	v_max_f32_e32 v114, 0, v114
	v_max_f32_e32 v115, 0, v115
	v_pk_mul_f32 v[124:125], v[124:125], v[124:125]
	v_pk_mul_f32 v[126:127], v[126:127], v[126:127]
	v_pk_mul_f32 v[120:121], v[120:121], v[120:121]
	v_pk_mul_f32 v[122:123], v[122:123], v[122:123]
	v_pk_mul_f32 v[116:117], v[116:117], v[116:117]
	v_pk_mul_f32 v[118:119], v[118:119], v[118:119]
	v_pk_mul_f32 v[112:113], v[112:113], v[112:113]
	v_pk_mul_f32 v[114:115], v[114:115], v[114:115]
	v_cvt_pk_bf16_f32 v124, v124, v125
	v_cvt_pk_bf16_f32 v125, v126, v127
	v_cvt_pk_bf16_f32 v126, v120, v121
	v_cvt_pk_bf16_f32 v127, v122, v123
	v_cvt_pk_bf16_f32 v116, v116, v117
	v_cvt_pk_bf16_f32 v117, v118, v119
	v_cvt_pk_bf16_f32 v118, v112, v113
	v_cvt_pk_bf16_f32 v119, v114, v115
	global_store_dwordx4 v224, v[124:127], s[48:49]
	global_store_dwordx4 v226, v[116:119], s[48:49]
	s_waitcnt vmcnt(8)
	v_fmamk_f32 v168, v168, 0x3a800000, v148
	v_rsq_f32_e32 v168, v168
	s_nop 0
	v_pk_mul_f32 v[108:109], v[108:109], v[168:169] op_sel_hi:[1,0]
	v_pk_mul_f32 v[110:111], v[110:111], v[168:169] op_sel_hi:[1,0]
	v_pk_mul_f32 v[104:105], v[104:105], v[168:169] op_sel_hi:[1,0]
	v_pk_mul_f32 v[106:107], v[106:107], v[168:169] op_sel_hi:[1,0]
	v_pk_mul_f32 v[100:101], v[100:101], v[168:169] op_sel_hi:[1,0]
	v_pk_mul_f32 v[102:103], v[102:103], v[168:169] op_sel_hi:[1,0]
	v_pk_mul_f32 v[96:97], v[96:97], v[168:169] op_sel_hi:[1,0]
	v_pk_mul_f32 v[98:99], v[98:99], v[168:169] op_sel_hi:[1,0]
	v_max_f32_e32 v108, 0, v108
	v_max_f32_e32 v109, 0, v109
	v_max_f32_e32 v110, 0, v110
	v_max_f32_e32 v111, 0, v111
	v_max_f32_e32 v104, 0, v104
	v_max_f32_e32 v105, 0, v105
	v_max_f32_e32 v106, 0, v106
	v_max_f32_e32 v107, 0, v107
	v_max_f32_e32 v100, 0, v100
	v_max_f32_e32 v101, 0, v101
	v_max_f32_e32 v102, 0, v102
	v_max_f32_e32 v103, 0, v103
	v_max_f32_e32 v96, 0, v96
	v_max_f32_e32 v97, 0, v97
	v_max_f32_e32 v98, 0, v98
	v_max_f32_e32 v99, 0, v99
	v_pk_mul_f32 v[108:109], v[108:109], v[108:109]
	v_pk_mul_f32 v[110:111], v[110:111], v[110:111]
	v_pk_mul_f32 v[104:105], v[104:105], v[104:105]
	v_pk_mul_f32 v[106:107], v[106:107], v[106:107]
	v_pk_mul_f32 v[100:101], v[100:101], v[100:101]
	v_pk_mul_f32 v[102:103], v[102:103], v[102:103]
	v_pk_mul_f32 v[96:97], v[96:97], v[96:97]
	v_pk_mul_f32 v[98:99], v[98:99], v[98:99]
	v_cvt_pk_bf16_f32 v108, v108, v109
	v_cvt_pk_bf16_f32 v109, v110, v111
	v_cvt_pk_bf16_f32 v110, v104, v105
	v_cvt_pk_bf16_f32 v111, v106, v107
	v_cvt_pk_bf16_f32 v100, v100, v101
	v_cvt_pk_bf16_f32 v101, v102, v103
	v_cvt_pk_bf16_f32 v102, v96, v97
	v_cvt_pk_bf16_f32 v103, v98, v99
	v_add_u32_e32 v225, 0x20000, v224
	v_add_u32_e32 v227, 0x20000, v226
	global_store_dwordx4 v225, v[108:111], s[48:49]
	global_store_dwordx4 v227, v[100:103], s[48:49]
	s_waitcnt vmcnt(9)
	v_fmamk_f32 v170, v170, 0x3a800000, v148
	v_rsq_f32_e32 v170, v170
	s_nop 0
	v_pk_mul_f32 v[92:93], v[92:93], v[170:171] op_sel_hi:[1,0]
	v_pk_mul_f32 v[94:95], v[94:95], v[170:171] op_sel_hi:[1,0]
	v_pk_mul_f32 v[88:89], v[88:89], v[170:171] op_sel_hi:[1,0]
	v_pk_mul_f32 v[90:91], v[90:91], v[170:171] op_sel_hi:[1,0]
	v_pk_mul_f32 v[84:85], v[84:85], v[170:171] op_sel_hi:[1,0]
	v_pk_mul_f32 v[86:87], v[86:87], v[170:171] op_sel_hi:[1,0]
	v_pk_mul_f32 v[80:81], v[80:81], v[170:171] op_sel_hi:[1,0]
	v_pk_mul_f32 v[82:83], v[82:83], v[170:171] op_sel_hi:[1,0]
	v_max_f32_e32 v92, 0, v92
	v_max_f32_e32 v93, 0, v93
	v_max_f32_e32 v94, 0, v94
	v_max_f32_e32 v95, 0, v95
	v_max_f32_e32 v88, 0, v88
	v_max_f32_e32 v89, 0, v89
	v_max_f32_e32 v90, 0, v90
	v_max_f32_e32 v91, 0, v91
	v_max_f32_e32 v84, 0, v84
	v_max_f32_e32 v85, 0, v85
	v_max_f32_e32 v86, 0, v86
	v_max_f32_e32 v87, 0, v87
	v_max_f32_e32 v80, 0, v80
	v_max_f32_e32 v81, 0, v81
	v_max_f32_e32 v82, 0, v82
	v_max_f32_e32 v83, 0, v83
	v_pk_mul_f32 v[92:93], v[92:93], v[92:93]
	v_pk_mul_f32 v[94:95], v[94:95], v[94:95]
	v_pk_mul_f32 v[88:89], v[88:89], v[88:89]
	v_pk_mul_f32 v[90:91], v[90:91], v[90:91]
	v_pk_mul_f32 v[84:85], v[84:85], v[84:85]
	v_pk_mul_f32 v[86:87], v[86:87], v[86:87]
	v_pk_mul_f32 v[80:81], v[80:81], v[80:81]
	v_pk_mul_f32 v[82:83], v[82:83], v[82:83]
	v_cvt_pk_bf16_f32 v92, v92, v93
	v_cvt_pk_bf16_f32 v93, v94, v95
	v_cvt_pk_bf16_f32 v94, v88, v89
	v_cvt_pk_bf16_f32 v95, v90, v91
	v_cvt_pk_bf16_f32 v84, v84, v85
	v_cvt_pk_bf16_f32 v85, v86, v87
	v_cvt_pk_bf16_f32 v86, v80, v81
	v_cvt_pk_bf16_f32 v87, v82, v83
	v_add_u32_e32 v225, 0x40000, v224
	v_add_u32_e32 v227, 0x40000, v226
	global_store_dwordx4 v225, v[92:95], s[48:49]
	global_store_dwordx4 v227, v[84:87], s[48:49]
	s_waitcnt vmcnt(10)
	v_fmamk_f32 v172, v172, 0x3a800000, v148
	v_rsq_f32_e32 v172, v172
	s_nop 0
	v_pk_mul_f32 v[76:77], v[76:77], v[172:173] op_sel_hi:[1,0]
	v_pk_mul_f32 v[78:79], v[78:79], v[172:173] op_sel_hi:[1,0]
	v_pk_mul_f32 v[72:73], v[72:73], v[172:173] op_sel_hi:[1,0]
	v_pk_mul_f32 v[74:75], v[74:75], v[172:173] op_sel_hi:[1,0]
	v_pk_mul_f32 v[68:69], v[68:69], v[172:173] op_sel_hi:[1,0]
	v_pk_mul_f32 v[70:71], v[70:71], v[172:173] op_sel_hi:[1,0]
	v_pk_mul_f32 v[64:65], v[64:65], v[172:173] op_sel_hi:[1,0]
	v_pk_mul_f32 v[66:67], v[66:67], v[172:173] op_sel_hi:[1,0]
	v_max_f32_e32 v76, 0, v76
	v_max_f32_e32 v77, 0, v77
	v_max_f32_e32 v78, 0, v78
	v_max_f32_e32 v79, 0, v79
	v_max_f32_e32 v72, 0, v72
	v_max_f32_e32 v73, 0, v73
	v_max_f32_e32 v74, 0, v74
	v_max_f32_e32 v75, 0, v75
	v_max_f32_e32 v68, 0, v68
	v_max_f32_e32 v69, 0, v69
	v_max_f32_e32 v70, 0, v70
	v_max_f32_e32 v71, 0, v71
	v_max_f32_e32 v64, 0, v64
	v_max_f32_e32 v65, 0, v65
	v_max_f32_e32 v66, 0, v66
	v_max_f32_e32 v67, 0, v67
	v_pk_mul_f32 v[76:77], v[76:77], v[76:77]
	v_pk_mul_f32 v[78:79], v[78:79], v[78:79]
	v_pk_mul_f32 v[72:73], v[72:73], v[72:73]
	v_pk_mul_f32 v[74:75], v[74:75], v[74:75]
	v_pk_mul_f32 v[68:69], v[68:69], v[68:69]
	v_pk_mul_f32 v[70:71], v[70:71], v[70:71]
	v_pk_mul_f32 v[64:65], v[64:65], v[64:65]
	v_pk_mul_f32 v[66:67], v[66:67], v[66:67]
	v_cvt_pk_bf16_f32 v76, v76, v77
	v_cvt_pk_bf16_f32 v77, v78, v79
	v_cvt_pk_bf16_f32 v78, v72, v73
	v_cvt_pk_bf16_f32 v79, v74, v75
	v_cvt_pk_bf16_f32 v68, v68, v69
	v_cvt_pk_bf16_f32 v69, v70, v71
	v_cvt_pk_bf16_f32 v70, v64, v65
	v_cvt_pk_bf16_f32 v71, v66, v67
	v_add_u32_e32 v225, 0x60000, v224
	v_add_u32_e32 v227, 0x60000, v226
	global_store_dwordx4 v225, v[76:79], s[48:49]
	global_store_dwordx4 v227, v[68:71], s[48:49]
	s_waitcnt vmcnt(11)
	v_fmamk_f32 v174, v174, 0x3a800000, v148
	v_rsq_f32_e32 v174, v174
	s_nop 0
	v_pk_mul_f32 v[60:61], v[60:61], v[174:175] op_sel_hi:[1,0]
	v_pk_mul_f32 v[62:63], v[62:63], v[174:175] op_sel_hi:[1,0]
	v_pk_mul_f32 v[56:57], v[56:57], v[174:175] op_sel_hi:[1,0]
	v_pk_mul_f32 v[58:59], v[58:59], v[174:175] op_sel_hi:[1,0]
	v_pk_mul_f32 v[52:53], v[52:53], v[174:175] op_sel_hi:[1,0]
	v_pk_mul_f32 v[54:55], v[54:55], v[174:175] op_sel_hi:[1,0]
	v_pk_mul_f32 v[48:49], v[48:49], v[174:175] op_sel_hi:[1,0]
	v_pk_mul_f32 v[50:51], v[50:51], v[174:175] op_sel_hi:[1,0]
	v_max_f32_e32 v60, 0, v60
	v_max_f32_e32 v61, 0, v61
	v_max_f32_e32 v62, 0, v62
	v_max_f32_e32 v63, 0, v63
	v_max_f32_e32 v56, 0, v56
	v_max_f32_e32 v57, 0, v57
	v_max_f32_e32 v58, 0, v58
	v_max_f32_e32 v59, 0, v59
	v_max_f32_e32 v52, 0, v52
	v_max_f32_e32 v53, 0, v53
	v_max_f32_e32 v54, 0, v54
	v_max_f32_e32 v55, 0, v55
	v_max_f32_e32 v48, 0, v48
	v_max_f32_e32 v49, 0, v49
	v_max_f32_e32 v50, 0, v50
	v_max_f32_e32 v51, 0, v51
	v_pk_mul_f32 v[60:61], v[60:61], v[60:61]
	v_pk_mul_f32 v[62:63], v[62:63], v[62:63]
	v_pk_mul_f32 v[56:57], v[56:57], v[56:57]
	v_pk_mul_f32 v[58:59], v[58:59], v[58:59]
	v_pk_mul_f32 v[52:53], v[52:53], v[52:53]
	v_pk_mul_f32 v[54:55], v[54:55], v[54:55]
	v_pk_mul_f32 v[48:49], v[48:49], v[48:49]
	v_pk_mul_f32 v[50:51], v[50:51], v[50:51]
	v_cvt_pk_bf16_f32 v60, v60, v61
	v_cvt_pk_bf16_f32 v61, v62, v63
	v_cvt_pk_bf16_f32 v62, v56, v57
	v_cvt_pk_bf16_f32 v63, v58, v59
	v_cvt_pk_bf16_f32 v52, v52, v53
	v_cvt_pk_bf16_f32 v53, v54, v55
	v_cvt_pk_bf16_f32 v54, v48, v49
	v_cvt_pk_bf16_f32 v55, v50, v51
	v_add_u32_e32 v225, 0x100000, v224
	v_add_u32_e32 v227, 0x100000, v226
	global_store_dwordx4 v225, v[60:63], s[48:49]
	global_store_dwordx4 v227, v[52:55], s[48:49]
	s_waitcnt vmcnt(12)
	v_fmamk_f32 v176, v176, 0x3a800000, v148
	v_rsq_f32_e32 v176, v176
	s_nop 0
	v_pk_mul_f32 v[44:45], v[44:45], v[176:177] op_sel_hi:[1,0]
	v_pk_mul_f32 v[46:47], v[46:47], v[176:177] op_sel_hi:[1,0]
	v_pk_mul_f32 v[40:41], v[40:41], v[176:177] op_sel_hi:[1,0]
	v_pk_mul_f32 v[42:43], v[42:43], v[176:177] op_sel_hi:[1,0]
	v_pk_mul_f32 v[36:37], v[36:37], v[176:177] op_sel_hi:[1,0]
	v_pk_mul_f32 v[38:39], v[38:39], v[176:177] op_sel_hi:[1,0]
	v_pk_mul_f32 v[32:33], v[32:33], v[176:177] op_sel_hi:[1,0]
	v_pk_mul_f32 v[34:35], v[34:35], v[176:177] op_sel_hi:[1,0]
	v_max_f32_e32 v44, 0, v44
	v_max_f32_e32 v45, 0, v45
	v_max_f32_e32 v46, 0, v46
	v_max_f32_e32 v47, 0, v47
	v_max_f32_e32 v40, 0, v40
	v_max_f32_e32 v41, 0, v41
	v_max_f32_e32 v42, 0, v42
	v_max_f32_e32 v43, 0, v43
	v_max_f32_e32 v36, 0, v36
	v_max_f32_e32 v37, 0, v37
	v_max_f32_e32 v38, 0, v38
	v_max_f32_e32 v39, 0, v39
	v_max_f32_e32 v32, 0, v32
	v_max_f32_e32 v33, 0, v33
	v_max_f32_e32 v34, 0, v34
	v_max_f32_e32 v35, 0, v35
	v_pk_mul_f32 v[44:45], v[44:45], v[44:45]
	v_pk_mul_f32 v[46:47], v[46:47], v[46:47]
	v_pk_mul_f32 v[40:41], v[40:41], v[40:41]
	v_pk_mul_f32 v[42:43], v[42:43], v[42:43]
	v_pk_mul_f32 v[36:37], v[36:37], v[36:37]
	v_pk_mul_f32 v[38:39], v[38:39], v[38:39]
	v_pk_mul_f32 v[32:33], v[32:33], v[32:33]
	v_pk_mul_f32 v[34:35], v[34:35], v[34:35]
	v_cvt_pk_bf16_f32 v44, v44, v45
	v_cvt_pk_bf16_f32 v45, v46, v47
	v_cvt_pk_bf16_f32 v46, v40, v41
	v_cvt_pk_bf16_f32 v47, v42, v43
	v_cvt_pk_bf16_f32 v36, v36, v37
	v_cvt_pk_bf16_f32 v37, v38, v39
	v_cvt_pk_bf16_f32 v38, v32, v33
	v_cvt_pk_bf16_f32 v39, v34, v35
	v_add_u32_e32 v225, 0x120000, v224
	v_add_u32_e32 v227, 0x120000, v226
	global_store_dwordx4 v225, v[44:47], s[48:49]
	global_store_dwordx4 v227, v[36:39], s[48:49]
	s_waitcnt vmcnt(13)
	v_fmamk_f32 v178, v178, 0x3a800000, v148
	v_rsq_f32_e32 v178, v178
	s_nop 0
	v_pk_mul_f32 v[28:29], v[28:29], v[178:179] op_sel_hi:[1,0]
	v_pk_mul_f32 v[30:31], v[30:31], v[178:179] op_sel_hi:[1,0]
	v_pk_mul_f32 v[24:25], v[24:25], v[178:179] op_sel_hi:[1,0]
	v_pk_mul_f32 v[26:27], v[26:27], v[178:179] op_sel_hi:[1,0]
	v_pk_mul_f32 v[20:21], v[20:21], v[178:179] op_sel_hi:[1,0]
	v_pk_mul_f32 v[22:23], v[22:23], v[178:179] op_sel_hi:[1,0]
	v_pk_mul_f32 v[16:17], v[16:17], v[178:179] op_sel_hi:[1,0]
	v_pk_mul_f32 v[18:19], v[18:19], v[178:179] op_sel_hi:[1,0]
	v_max_f32_e32 v28, 0, v28
	v_max_f32_e32 v29, 0, v29
	v_max_f32_e32 v30, 0, v30
	v_max_f32_e32 v31, 0, v31
	v_max_f32_e32 v24, 0, v24
	v_max_f32_e32 v25, 0, v25
	v_max_f32_e32 v26, 0, v26
	v_max_f32_e32 v27, 0, v27
	v_max_f32_e32 v20, 0, v20
	v_max_f32_e32 v21, 0, v21
	v_max_f32_e32 v22, 0, v22
	v_max_f32_e32 v23, 0, v23
	v_max_f32_e32 v16, 0, v16
	v_max_f32_e32 v17, 0, v17
	v_max_f32_e32 v18, 0, v18
	v_max_f32_e32 v19, 0, v19
	v_pk_mul_f32 v[28:29], v[28:29], v[28:29]
	v_pk_mul_f32 v[30:31], v[30:31], v[30:31]
	v_pk_mul_f32 v[24:25], v[24:25], v[24:25]
	v_pk_mul_f32 v[26:27], v[26:27], v[26:27]
	v_pk_mul_f32 v[20:21], v[20:21], v[20:21]
	v_pk_mul_f32 v[22:23], v[22:23], v[22:23]
	v_pk_mul_f32 v[16:17], v[16:17], v[16:17]
	v_pk_mul_f32 v[18:19], v[18:19], v[18:19]
	v_cvt_pk_bf16_f32 v28, v28, v29
	v_cvt_pk_bf16_f32 v29, v30, v31
	v_cvt_pk_bf16_f32 v30, v24, v25
	v_cvt_pk_bf16_f32 v31, v26, v27
	v_cvt_pk_bf16_f32 v20, v20, v21
	v_cvt_pk_bf16_f32 v21, v22, v23
	v_cvt_pk_bf16_f32 v22, v16, v17
	v_cvt_pk_bf16_f32 v23, v18, v19
	v_add_u32_e32 v225, 0x140000, v224
	v_add_u32_e32 v227, 0x140000, v226
	global_store_dwordx4 v225, v[28:31], s[48:49]
	global_store_dwordx4 v227, v[20:23], s[48:49]
	s_waitcnt vmcnt(14)
	v_fmamk_f32 v180, v180, 0x3a800000, v148
	v_rsq_f32_e32 v180, v180
	s_nop 0
	v_pk_mul_f32 v[12:13], v[12:13], v[180:181] op_sel_hi:[1,0]
	v_pk_mul_f32 v[14:15], v[14:15], v[180:181] op_sel_hi:[1,0]
	v_pk_mul_f32 v[8:9], v[8:9], v[180:181] op_sel_hi:[1,0]
	v_pk_mul_f32 v[10:11], v[10:11], v[180:181] op_sel_hi:[1,0]
	v_pk_mul_f32 v[4:5], v[4:5], v[180:181] op_sel_hi:[1,0]
	v_pk_mul_f32 v[6:7], v[6:7], v[180:181] op_sel_hi:[1,0]
	v_pk_mul_f32 v[0:1], v[0:1], v[180:181] op_sel_hi:[1,0]
	v_pk_mul_f32 v[2:3], v[2:3], v[180:181] op_sel_hi:[1,0]
	v_max_f32_e32 v12, 0, v12
	v_max_f32_e32 v13, 0, v13
	v_max_f32_e32 v14, 0, v14
	v_max_f32_e32 v15, 0, v15
	v_max_f32_e32 v8, 0, v8
	v_max_f32_e32 v9, 0, v9
	v_max_f32_e32 v10, 0, v10
	v_max_f32_e32 v11, 0, v11
	v_max_f32_e32 v4, 0, v4
	v_max_f32_e32 v5, 0, v5
	v_max_f32_e32 v6, 0, v6
	v_max_f32_e32 v7, 0, v7
	v_max_f32_e32 v0, 0, v0
	v_max_f32_e32 v1, 0, v1
	v_max_f32_e32 v2, 0, v2
	v_max_f32_e32 v3, 0, v3
	v_pk_mul_f32 v[12:13], v[12:13], v[12:13]
	v_pk_mul_f32 v[14:15], v[14:15], v[14:15]
	v_pk_mul_f32 v[8:9], v[8:9], v[8:9]
	v_pk_mul_f32 v[10:11], v[10:11], v[10:11]
	v_pk_mul_f32 v[4:5], v[4:5], v[4:5]
	v_pk_mul_f32 v[6:7], v[6:7], v[6:7]
	v_pk_mul_f32 v[0:1], v[0:1], v[0:1]
	v_pk_mul_f32 v[2:3], v[2:3], v[2:3]
	v_cvt_pk_bf16_f32 v12, v12, v13
	v_cvt_pk_bf16_f32 v13, v14, v15
	v_cvt_pk_bf16_f32 v14, v8, v9
	v_cvt_pk_bf16_f32 v15, v10, v11
	v_cvt_pk_bf16_f32 v4, v4, v5
	v_cvt_pk_bf16_f32 v5, v6, v7
	v_cvt_pk_bf16_f32 v6, v0, v1
	v_cvt_pk_bf16_f32 v7, v2, v3
	v_add_u32_e32 v225, 0x160000, v224
	v_add_u32_e32 v227, 0x160000, v226
	global_store_dwordx4 v225, v[12:15], s[48:49]
	global_store_dwordx4 v227, v[4:7], s[48:49]
	s_mov_b32 s11, 0x160000
	s_andn2_b64 vcc, exec, s[36:37]
	s_mov_b64 s[14:15], -1
	s_cbranch_vccnz .LBB0_656
	s_andn2_b64 vcc, exec, s[4:5]
	s_cbranch_vccnz .LBB0_655
	s_barrier
	s_branch .LBB0_655

.LBB0_721:
	v_bfe_i32 v3, v0, 27, 1
	v_lshlrev_b32_e32 v1, 4, v0
	v_lshrrev_b32_e32 v3, 22, v3
	v_add_u32_e32 v3, v1, v3
	v_and_b32_e32 v3, 0xfffffc00, v3
	v_sub_u32_e32 v3, v1, v3
	v_ashrrev_i32_e32 v2, 31, v0
	v_lshrrev_b32_e32 v4, 4, v3
	v_lshrrev_b32_e32 v2, 26, v2
	v_bitop3_b32 v3, v4, v3, 32 bitop3:0x6c
	v_add_u32_e32 v2, v0, v2
	v_ashrrev_i32_e32 v5, 31, v3
	v_ashrrev_i32_e32 v2, 6, v2
	v_lshrrev_b32_e32 v5, 26, v5
	v_lshlrev_b32_e32 v4, 3, v2
	v_add_u32_e32 v5, v3, v5
	v_and_b32_e32 v4, -16, v4
	v_ashrrev_i32_e32 v6, 6, v5
	v_and_b32_e32 v5, 0xc0, v5
	v_add_u32_e32 v4, v6, v4
	v_sub_u32_e32 v3, v3, v5
	v_lshlrev_b32_e32 v2, 5, v2
	v_ashrrev_i16_sdwa v3, v149, sext(v3) dst_sel:DWORD dst_unused:UNUSED_PAD src0_sel:DWORD src1_sel:BYTE_0
	v_lshlrev_b32_e32 v5, 1, v4
	v_lshrrev_b32_e32 v7, 2, v4
	v_and_b32_e32 v6, 3, v6
	s_mov_b32 s0, 0x7ffe0
	v_and_b32_e32 v2, 32, v2
	v_bfe_i32 v3, v3, 0, 16
	v_and_b32_e32 v5, 24, v5
	v_and_b32_e32 v7, 4, v7
	v_and_or_b32 v6, v4, s0, v6
	v_or3_b32 v5, v6, v7, v5
	v_add_lshl_u32 v2, v2, v3, 1
	v_add_u32_e32 v1, 0x2000, v1
	v_lshl_add_u32 v132, v4, 13, v2
	v_lshl_add_u32 v146, v5, 13, v2
	v_ashrrev_i32_e32 v2, 31, v1
	v_lshrrev_b32_e32 v2, 22, v2
	v_add_u32_e32 v2, v1, v2
	v_ashrrev_i32_e32 v2, 10, v2
	v_mul_i32_i24_e32 v3, 0x400, v2
	v_sub_u32_e32 v1, v1, v3
	v_lshrrev_b32_e32 v3, 4, v1
	v_bitop3_b32 v1, v3, v1, 32 bitop3:0x6c
	v_ashrrev_i32_e32 v4, 31, v1
	v_lshrrev_b32_e32 v4, 26, v4
	v_lshlrev_b32_e32 v3, 3, v2
	v_add_u32_e32 v4, v1, v4
	v_and_b32_e32 v3, -16, v3
	v_ashrrev_i32_e32 v5, 6, v4
	v_and_b32_e32 v4, 0xc0, v4
	v_add_u32_e32 v3, v5, v3
	v_sub_u32_e32 v1, v1, v4
	v_and_b32_e32 v5, 3, v5
	s_ashr_i32 s8, s6, 6
	v_lshlrev_b32_e32 v2, 5, v2
	v_ashrrev_i16_sdwa v1, v149, sext(v1) dst_sel:DWORD dst_unused:UNUSED_PAD src0_sel:DWORD src1_sel:BYTE_0
	v_lshlrev_b32_e32 v4, 1, v3
	v_lshrrev_b32_e32 v6, 2, v3
	v_and_or_b32 v5, v3, s0, v5
	s_lshl_b32 s0, s8, 10
	v_and_b32_e32 v2, 32, v2
	v_bfe_i32 v1, v1, 0, 16
	v_and_b32_e32 v4, 24, v4
	v_and_b32_e32 v6, 4, v6
	s_add_i32 s38, s0, 0
	v_or3_b32 v4, v5, v6, v4
	v_add_lshl_u32 v1, v2, v1, 1
	s_add_i32 s39, s38, 0x10000
	s_mov_b32 s0, m0
	s_mov_b32 m0, s39
	s_nop 0
	global_load_lds_dwordx4 v146, s[84:85]
	s_mov_b32 m0, s0
	v_lshl_add_u32 v150, v4, 13, v1
	s_add_i32 s40, s38, 0x12000
	s_mov_b32 s0, m0
	s_mov_b32 m0, s40
	s_nop 0
	global_load_lds_dwordx4 v150, s[84:85]
	s_mov_b32 m0, s0
	v_readlane_b32 s10, v243, 63
	s_add_i32 s41, s38, 0x14000
	v_readlane_b32 s11, v242, 0
	s_mov_b32 s0, m0
	s_mov_b32 m0, s41
	s_nop 0
	global_load_lds_dwordx4 v146, s[10:11]
	s_mov_b32 m0, s0
	s_add_i32 s65, s38, 0x16000
	s_mov_b32 s0, m0
	s_mov_b32 m0, s65
	s_nop 0
	global_load_lds_dwordx4 v150, s[10:11]
	s_mov_b32 m0, s0
	v_and_b32_e32 v132, 0x7f, v165
	v_lshlrev_b32_e32 v132, 4, v132
	v_and_b32_e32 v147, 0x180, v165
	v_lshl_or_b32 v132, v147, 10, v132
	v_add_u32_e32 v147, 0x80000, v132
	s_mov_b32 s0, m0
	s_mov_b32 m0, s38
	s_nop 0
	global_load_lds_dwordx4 v132, s[88:89]
	s_mov_b32 m0, s0
	s_add_i32 s35, s38, 0x2000
	s_mov_b32 s0, m0
	s_mov_b32 m0, s35
	s_nop 0
	global_load_lds_dwordx4 v147, s[88:89]
	s_mov_b32 m0, s0
	v_readlane_b32 s10, v242, 1
	s_add_i32 s30, s38, 0x4000
	v_readlane_b32 s11, v242, 2
	s_mov_b32 s0, m0
	s_mov_b32 m0, s30
	s_nop 0
	global_load_lds_dwordx4 v132, s[10:11]
	s_mov_b32 m0, s0
	s_ashr_i32 s7, s6, 8
	s_add_i32 s31, s38, 0x6000
	s_mov_b32 s0, m0
	s_mov_b32 m0, s31
	s_nop 0
	global_load_lds_dwordx4 v147, s[10:11]
	s_mov_b32 m0, s0
	s_cmp_eq_u32 s7, 1
	s_cselect_b64 s[0:1], -1, 0
	s_cmp_lg_u32 s7, 1
	s_cbranch_scc1 .LBB0_723
	s_barrier

.LBB0_732:
	s_ashr_i32 s11, s10, 31
	s_lshl_b64 s[12:13], s[10:11], 21
	s_add_u32 s12, s48, s12
	s_addc_u32 s13, s49, s13
	s_and_b64 s[14:15], s[36:37], exec
	s_cselect_b32 s11, s13, s17
	s_cselect_b32 vcc_lo, s12, s16
	s_ashr_i32 s9, s8, 31
	s_lshl_b64 s[14:15], s[8:9], 21
	s_add_u32 s14, s33, s14
	s_addc_u32 s15, s28, s15
	s_and_b64 s[20:21], s[36:37], exec
	s_cselect_b32 s9, s15, s19
	s_cselect_b32 s78, s14, s18
	s_add_u32 s79, s18, 0x100
	s_addc_u32 vcc_hi, s19, 0
	s_mov_b32 s80, -2
	v_add_u32_e32 v155, 0x10000, v153
	ds_read_b128 v[142:145], v155
	ds_read_b128 v[156:159], v155 offset:1024
	ds_read_b128 v[160:163], v155 offset:2048
	ds_read_b128 v[166:169], v155 offset:3072
	v_add_u32_e32 v155, 0x14000, v153
	ds_read_b128 v[170:173], v155
	ds_read_b128 v[174:177], v155 offset:1024
	ds_read_b128 v[178:181], v155 offset:2048
	ds_read_b128 v[182:185], v155 offset:3072
	s_add_u32 s18, s16, 0x1000
	s_addc_u32 s19, s17, 0
	s_cmp_eq_u32 s80, 60
	s_cselect_b32 s24, vcc_lo, s18
	s_cselect_b32 s25, s11, s19
	s_cselect_b32 s22, s78, s79
	s_cselect_b32 s23, s9, vcc_hi
	s_add_u32 s20, s24, 0x800
	s_addc_u32 s21, s25, 0
	ds_read_b128 v[186:189], v154
	ds_read_b128 v[190:193], v154 offset:1024
	ds_read_b128 v[194:197], v154 offset:2048
	ds_read_b128 v[198:201], v154 offset:3072
	ds_read_b128 v[202:205], v154 offset:4096
	ds_read_b128 v[206:209], v154 offset:5120
	ds_read_b128 v[210:213], v154 offset:6144
	ds_read_b128 v[214:217], v154 offset:7168
	s_add_u32 s16, s16, 0x100800
	s_addc_u32 s17, s17, 0
	s_mov_b32 s81, m0
	s_mov_b32 m0, s83
	s_nop 0
	global_load_lds_dwordx4 v132, s[16:17]
	s_mov_b32 m0, s81
	s_add_i32 s81, s38, 0xe000
	s_mov_b32 s86, m0
	s_mov_b32 m0, s81
	s_nop 0
	global_load_lds_dwordx4 v147, s[16:17]
	s_mov_b32 m0, s86
	s_waitcnt vmcnt(8)
	s_waitcnt lgkmcnt(0)
	s_barrier
	s_setprio 1
	s_waitcnt lgkmcnt(7)
	v_mfma_f32_16x16x32_bf16 v[124:127], v[142:145], v[186:189], 0
	v_mfma_f32_16x16x32_bf16 v[120:123], v[160:163], v[186:189], 0
	s_waitcnt lgkmcnt(5)
	v_mfma_f32_16x16x32_bf16 v[108:111], v[142:145], v[194:197], 0
	v_mfma_f32_16x16x32_bf16 v[104:107], v[160:163], v[194:197], 0
	s_waitcnt lgkmcnt(3)
	v_mfma_f32_16x16x32_bf16 v[92:95], v[142:145], v[202:205], 0
	v_mfma_f32_16x16x32_bf16 v[88:91], v[160:163], v[202:205], 0
	s_waitcnt lgkmcnt(1)
	v_mfma_f32_16x16x32_bf16 v[76:79], v[142:145], v[210:213], 0
	v_mfma_f32_16x16x32_bf16 v[72:75], v[160:163], v[210:213], 0
	v_mfma_f32_16x16x32_bf16 v[124:127], v[156:159], v[190:193], v[124:127]
	v_mfma_f32_16x16x32_bf16 v[120:123], v[166:169], v[190:193], v[120:123]
	v_mfma_f32_16x16x32_bf16 v[108:111], v[156:159], v[198:201], v[108:111]
	v_mfma_f32_16x16x32_bf16 v[104:107], v[166:169], v[198:201], v[104:107]
	v_mfma_f32_16x16x32_bf16 v[92:95], v[156:159], v[206:209], v[92:95]
	v_mfma_f32_16x16x32_bf16 v[88:91], v[166:169], v[206:209], v[88:91]
	s_waitcnt lgkmcnt(0)
	v_mfma_f32_16x16x32_bf16 v[76:79], v[156:159], v[214:217], v[76:79]
	v_mfma_f32_16x16x32_bf16 v[72:75], v[166:169], v[214:217], v[72:75]
	s_setprio 0
	s_setprio 1
	v_mfma_f32_16x16x32_bf16 v[116:119], v[170:173], v[186:189], 0
	v_mfma_f32_16x16x32_bf16 v[112:115], v[178:181], v[186:189], 0
	v_mfma_f32_16x16x32_bf16 v[100:103], v[170:173], v[194:197], 0
	v_mfma_f32_16x16x32_bf16 v[96:99], v[178:181], v[194:197], 0
	v_mfma_f32_16x16x32_bf16 v[84:87], v[170:173], v[202:205], 0
	v_mfma_f32_16x16x32_bf16 v[80:83], v[178:181], v[202:205], 0
	v_mfma_f32_16x16x32_bf16 v[68:71], v[170:173], v[210:213], 0
	v_mfma_f32_16x16x32_bf16 v[64:67], v[178:181], v[210:213], 0
	v_mfma_f32_16x16x32_bf16 v[116:119], v[174:177], v[190:193], v[116:119]
	v_mfma_f32_16x16x32_bf16 v[112:115], v[182:185], v[190:193], v[112:115]
	v_mfma_f32_16x16x32_bf16 v[100:103], v[174:177], v[198:201], v[100:103]
	v_mfma_f32_16x16x32_bf16 v[96:99], v[182:185], v[198:201], v[96:99]
	v_mfma_f32_16x16x32_bf16 v[84:87], v[174:177], v[206:209], v[84:87]
	v_mfma_f32_16x16x32_bf16 v[80:83], v[182:185], v[206:209], v[80:83]
	v_mfma_f32_16x16x32_bf16 v[68:71], v[174:177], v[214:217], v[68:71]
	v_mfma_f32_16x16x32_bf16 v[64:67], v[182:185], v[214:217], v[64:67]
	s_setprio 0
	s_barrier
	ds_read_b128 v[186:189], v154 offset:16384
	ds_read_b128 v[190:193], v154 offset:17408
	ds_read_b128 v[194:197], v154 offset:18432
	ds_read_b128 v[198:201], v154 offset:19456
	ds_read_b128 v[202:205], v154 offset:20480
	ds_read_b128 v[206:209], v154 offset:21504
	ds_read_b128 v[210:213], v154 offset:22528
	ds_read_b128 v[214:217], v154 offset:23552
	s_mov_b32 s16, m0
	s_mov_b32 m0, s39
	s_nop 0
	global_load_lds_dwordx4 v146, s[22:23]
	s_mov_b32 m0, s16
	s_nop 0
	s_mov_b32 s16, m0
	s_mov_b32 m0, s40
	s_nop 0
	global_load_lds_dwordx4 v150, s[22:23]
	s_mov_b32 m0, s16
	s_add_u32 s16, s22, 0x100000
	s_addc_u32 s17, s23, 0
	s_mov_b32 s81, m0
	s_mov_b32 m0, s41
	s_nop 0
	global_load_lds_dwordx4 v146, s[16:17]
	s_mov_b32 m0, s81
	s_nop 0
	s_mov_b32 s81, m0
	s_mov_b32 m0, s65
	s_nop 0
	global_load_lds_dwordx4 v150, s[16:17]
	s_mov_b32 m0, s81
	s_mov_b32 s16, m0
	s_mov_b32 m0, s38
	s_nop 0
	global_load_lds_dwordx4 v132, s[24:25]
	s_mov_b32 m0, s16
	s_nop 0
	s_mov_b32 s16, m0
	s_mov_b32 m0, s35
	s_nop 0
	global_load_lds_dwordx4 v147, s[24:25]
	s_mov_b32 m0, s16
	s_waitcnt vmcnt(8)
	s_waitcnt lgkmcnt(0)
	s_barrier
	s_setprio 1
	s_waitcnt lgkmcnt(7)
	v_mfma_f32_16x16x32_bf16 v[60:63], v[142:145], v[186:189], 0
	v_mfma_f32_16x16x32_bf16 v[56:59], v[160:163], v[186:189], 0
	s_waitcnt lgkmcnt(5)
	v_mfma_f32_16x16x32_bf16 v[44:47], v[142:145], v[194:197], 0
	v_mfma_f32_16x16x32_bf16 v[40:43], v[160:163], v[194:197], 0
	s_waitcnt lgkmcnt(3)
	v_mfma_f32_16x16x32_bf16 v[28:31], v[142:145], v[202:205], 0
	v_mfma_f32_16x16x32_bf16 v[24:27], v[160:163], v[202:205], 0
	s_waitcnt lgkmcnt(1)
	v_mfma_f32_16x16x32_bf16 v[12:15], v[142:145], v[210:213], 0
	v_mfma_f32_16x16x32_bf16 v[8:11], v[160:163], v[210:213], 0
	v_mfma_f32_16x16x32_bf16 v[60:63], v[156:159], v[190:193], v[60:63]
	v_mfma_f32_16x16x32_bf16 v[56:59], v[166:169], v[190:193], v[56:59]
	v_mfma_f32_16x16x32_bf16 v[44:47], v[156:159], v[198:201], v[44:47]
	v_mfma_f32_16x16x32_bf16 v[40:43], v[166:169], v[198:201], v[40:43]
	v_mfma_f32_16x16x32_bf16 v[28:31], v[156:159], v[206:209], v[28:31]
	v_mfma_f32_16x16x32_bf16 v[24:27], v[166:169], v[206:209], v[24:27]
	s_waitcnt lgkmcnt(0)
	v_mfma_f32_16x16x32_bf16 v[12:15], v[156:159], v[214:217], v[12:15]
	v_mfma_f32_16x16x32_bf16 v[8:11], v[166:169], v[214:217], v[8:11]
	s_setprio 0
	s_setprio 1
	v_mfma_f32_16x16x32_bf16 v[52:55], v[170:173], v[186:189], 0
	v_mfma_f32_16x16x32_bf16 v[48:51], v[178:181], v[186:189], 0
	v_mfma_f32_16x16x32_bf16 v[36:39], v[170:173], v[194:197], 0
	v_mfma_f32_16x16x32_bf16 v[32:35], v[178:181], v[194:197], 0
	v_mfma_f32_16x16x32_bf16 v[20:23], v[170:173], v[202:205], 0
	v_mfma_f32_16x16x32_bf16 v[16:19], v[178:181], v[202:205], 0
	v_mfma_f32_16x16x32_bf16 v[4:7], v[170:173], v[210:213], 0
	v_mfma_f32_16x16x32_bf16 v[0:3], v[178:181], v[210:213], 0
	v_mfma_f32_16x16x32_bf16 v[52:55], v[174:177], v[190:193], v[52:55]
	v_mfma_f32_16x16x32_bf16 v[48:51], v[182:185], v[190:193], v[48:51]
	v_mfma_f32_16x16x32_bf16 v[36:39], v[174:177], v[198:201], v[36:39]
	v_mfma_f32_16x16x32_bf16 v[32:35], v[182:185], v[198:201], v[32:35]
	v_mfma_f32_16x16x32_bf16 v[20:23], v[174:177], v[206:209], v[20:23]
	v_mfma_f32_16x16x32_bf16 v[16:19], v[182:185], v[206:209], v[16:19]
	v_mfma_f32_16x16x32_bf16 v[4:7], v[174:177], v[214:217], v[4:7]
	v_mfma_f32_16x16x32_bf16 v[0:3], v[182:185], v[214:217], v[0:3]
	s_setprio 0
	s_barrier
	v_add_u32_e32 v155, 0x18000, v153
	ds_read_b128 v[142:145], v155
	ds_read_b128 v[156:159], v155 offset:1024
	ds_read_b128 v[160:163], v155 offset:2048
	ds_read_b128 v[166:169], v155 offset:3072
	v_add_u32_e32 v155, 0x1c000, v153
	ds_read_b128 v[170:173], v155
	ds_read_b128 v[174:177], v155 offset:1024
	ds_read_b128 v[178:181], v155 offset:2048
	ds_read_b128 v[182:185], v155 offset:3072
	ds_read_b128 v[186:189], v154 offset:32768
	ds_read_b128 v[190:193], v154 offset:33792
	ds_read_b128 v[194:197], v154 offset:34816
	ds_read_b128 v[198:201], v154 offset:35840
	ds_read_b128 v[202:205], v154 offset:36864
	ds_read_b128 v[206:209], v154 offset:37888
	ds_read_b128 v[210:213], v154 offset:38912
	ds_read_b128 v[214:217], v154 offset:39936
	s_add_u32 s16, s24, 0x100000
	s_addc_u32 s17, s25, 0
	s_mov_b32 s24, m0
	s_mov_b32 m0, s30
	s_nop 0
	global_load_lds_dwordx4 v132, s[16:17]
	s_mov_b32 m0, s24
	s_nop 0
	s_mov_b32 s24, m0
	s_mov_b32 m0, s31
	s_nop 0
	global_load_lds_dwordx4 v147, s[16:17]
	s_mov_b32 m0, s24
	s_waitcnt vmcnt(8)
	s_waitcnt lgkmcnt(0)
	s_barrier
	s_setprio 1
	s_waitcnt lgkmcnt(7)
	v_mfma_f32_16x16x32_bf16 v[124:127], v[142:145], v[186:189], v[124:127]
	v_mfma_f32_16x16x32_bf16 v[120:123], v[160:163], v[186:189], v[120:123]
	s_waitcnt lgkmcnt(5)
	v_mfma_f32_16x16x32_bf16 v[108:111], v[142:145], v[194:197], v[108:111]
	v_mfma_f32_16x16x32_bf16 v[104:107], v[160:163], v[194:197], v[104:107]
	s_waitcnt lgkmcnt(3)
	v_mfma_f32_16x16x32_bf16 v[92:95], v[142:145], v[202:205], v[92:95]
	v_mfma_f32_16x16x32_bf16 v[88:91], v[160:163], v[202:205], v[88:91]
	s_waitcnt lgkmcnt(1)
	v_mfma_f32_16x16x32_bf16 v[76:79], v[142:145], v[210:213], v[76:79]
	v_mfma_f32_16x16x32_bf16 v[72:75], v[160:163], v[210:213], v[72:75]
	v_mfma_f32_16x16x32_bf16 v[124:127], v[156:159], v[190:193], v[124:127]
	v_mfma_f32_16x16x32_bf16 v[120:123], v[166:169], v[190:193], v[120:123]
	v_mfma_f32_16x16x32_bf16 v[108:111], v[156:159], v[198:201], v[108:111]
	v_mfma_f32_16x16x32_bf16 v[104:107], v[166:169], v[198:201], v[104:107]
	v_mfma_f32_16x16x32_bf16 v[92:95], v[156:159], v[206:209], v[92:95]
	v_mfma_f32_16x16x32_bf16 v[88:91], v[166:169], v[206:209], v[88:91]
	s_waitcnt lgkmcnt(0)
	v_mfma_f32_16x16x32_bf16 v[76:79], v[156:159], v[214:217], v[76:79]
	v_mfma_f32_16x16x32_bf16 v[72:75], v[166:169], v[214:217], v[72:75]
	s_setprio 0
	s_setprio 1
	v_mfma_f32_16x16x32_bf16 v[116:119], v[170:173], v[186:189], v[116:119]
	v_mfma_f32_16x16x32_bf16 v[112:115], v[178:181], v[186:189], v[112:115]
	v_mfma_f32_16x16x32_bf16 v[100:103], v[170:173], v[194:197], v[100:103]
	v_mfma_f32_16x16x32_bf16 v[96:99], v[178:181], v[194:197], v[96:99]
	v_mfma_f32_16x16x32_bf16 v[84:87], v[170:173], v[202:205], v[84:87]
	v_mfma_f32_16x16x32_bf16 v[80:83], v[178:181], v[202:205], v[80:83]
	v_mfma_f32_16x16x32_bf16 v[68:71], v[170:173], v[210:213], v[68:71]
	v_mfma_f32_16x16x32_bf16 v[64:67], v[178:181], v[210:213], v[64:67]
	v_mfma_f32_16x16x32_bf16 v[116:119], v[174:177], v[190:193], v[116:119]
	v_mfma_f32_16x16x32_bf16 v[112:115], v[182:185], v[190:193], v[112:115]
	v_mfma_f32_16x16x32_bf16 v[100:103], v[174:177], v[198:201], v[100:103]
	v_mfma_f32_16x16x32_bf16 v[96:99], v[182:185], v[198:201], v[96:99]
	v_mfma_f32_16x16x32_bf16 v[84:87], v[174:177], v[206:209], v[84:87]
	v_mfma_f32_16x16x32_bf16 v[80:83], v[182:185], v[206:209], v[80:83]
	v_mfma_f32_16x16x32_bf16 v[68:71], v[174:177], v[214:217], v[68:71]
	v_mfma_f32_16x16x32_bf16 v[64:67], v[182:185], v[214:217], v[64:67]
	s_setprio 0
	s_barrier
	ds_read_b128 v[186:189], v154 offset:49152
	ds_read_b128 v[190:193], v154 offset:50176
	ds_read_b128 v[194:197], v154 offset:51200
	ds_read_b128 v[198:201], v154 offset:52224
	ds_read_b128 v[202:205], v154 offset:53248
	ds_read_b128 v[206:209], v154 offset:54272
	ds_read_b128 v[210:213], v154 offset:55296
	ds_read_b128 v[214:217], v154 offset:56320
	s_add_u32 s16, s22, 0x80
	s_addc_u32 s17, s23, 0
	s_mov_b32 s24, m0
	s_mov_b32 m0, s64
	s_nop 0
	global_load_lds_dwordx4 v146, s[16:17]
	s_mov_b32 m0, s24
	s_nop 0
	s_mov_b32 s24, m0
	s_mov_b32 m0, s82
	s_nop 0
	global_load_lds_dwordx4 v150, s[16:17]
	s_mov_b32 m0, s24
	s_add_u32 s16, s22, 0x100080
	s_addc_u32 s17, s23, 0
	s_mov_b32 s22, m0
	s_mov_b32 m0, s66
	s_nop 0
	global_load_lds_dwordx4 v146, s[16:17]
	s_mov_b32 m0, s22
	s_nop 0
	s_mov_b32 s22, m0
	s_mov_b32 m0, s67
	s_nop 0
	global_load_lds_dwordx4 v150, s[16:17]
	s_mov_b32 m0, s22
	s_mov_b32 s16, m0
	s_mov_b32 m0, s44
	s_nop 0
	global_load_lds_dwordx4 v132, s[20:21]
	s_mov_b32 m0, s16
	s_nop 0
	s_mov_b32 s16, m0
	s_mov_b32 m0, s45
	s_nop 0
	global_load_lds_dwordx4 v147, s[20:21]
	s_mov_b32 m0, s16
	s_waitcnt vmcnt(8)
	s_waitcnt lgkmcnt(0)
	s_barrier
	s_setprio 1
	s_waitcnt lgkmcnt(7)
	v_mfma_f32_16x16x32_bf16 v[60:63], v[142:145], v[186:189], v[60:63]
	v_mfma_f32_16x16x32_bf16 v[56:59], v[160:163], v[186:189], v[56:59]
	s_waitcnt lgkmcnt(5)
	v_mfma_f32_16x16x32_bf16 v[44:47], v[142:145], v[194:197], v[44:47]
	v_mfma_f32_16x16x32_bf16 v[40:43], v[160:163], v[194:197], v[40:43]
	s_waitcnt lgkmcnt(3)
	v_mfma_f32_16x16x32_bf16 v[28:31], v[142:145], v[202:205], v[28:31]
	v_mfma_f32_16x16x32_bf16 v[24:27], v[160:163], v[202:205], v[24:27]
	s_waitcnt lgkmcnt(1)
	v_mfma_f32_16x16x32_bf16 v[12:15], v[142:145], v[210:213], v[12:15]
	v_mfma_f32_16x16x32_bf16 v[8:11], v[160:163], v[210:213], v[8:11]
	v_mfma_f32_16x16x32_bf16 v[60:63], v[156:159], v[190:193], v[60:63]
	v_mfma_f32_16x16x32_bf16 v[56:59], v[166:169], v[190:193], v[56:59]
	v_mfma_f32_16x16x32_bf16 v[44:47], v[156:159], v[198:201], v[44:47]
	v_mfma_f32_16x16x32_bf16 v[40:43], v[166:169], v[198:201], v[40:43]
	v_mfma_f32_16x16x32_bf16 v[28:31], v[156:159], v[206:209], v[28:31]
	v_mfma_f32_16x16x32_bf16 v[24:27], v[166:169], v[206:209], v[24:27]
	s_waitcnt lgkmcnt(0)
	v_mfma_f32_16x16x32_bf16 v[12:15], v[156:159], v[214:217], v[12:15]
	v_mfma_f32_16x16x32_bf16 v[8:11], v[166:169], v[214:217], v[8:11]
	s_setprio 0
	s_setprio 1
	v_mfma_f32_16x16x32_bf16 v[52:55], v[170:173], v[186:189], v[52:55]
	v_mfma_f32_16x16x32_bf16 v[48:51], v[178:181], v[186:189], v[48:51]
	v_mfma_f32_16x16x32_bf16 v[36:39], v[170:173], v[194:197], v[36:39]
	v_mfma_f32_16x16x32_bf16 v[32:35], v[178:181], v[194:197], v[32:35]
	v_mfma_f32_16x16x32_bf16 v[20:23], v[170:173], v[202:205], v[20:23]
	v_mfma_f32_16x16x32_bf16 v[16:19], v[178:181], v[202:205], v[16:19]
	v_mfma_f32_16x16x32_bf16 v[4:7], v[170:173], v[210:213], v[4:7]
	v_mfma_f32_16x16x32_bf16 v[0:3], v[178:181], v[210:213], v[0:3]
	v_mfma_f32_16x16x32_bf16 v[52:55], v[174:177], v[190:193], v[52:55]
	v_mfma_f32_16x16x32_bf16 v[48:51], v[182:185], v[190:193], v[48:51]
	v_mfma_f32_16x16x32_bf16 v[36:39], v[174:177], v[198:201], v[36:39]
	v_mfma_f32_16x16x32_bf16 v[32:35], v[182:185], v[198:201], v[32:35]
	v_mfma_f32_16x16x32_bf16 v[20:23], v[174:177], v[206:209], v[20:23]
	v_mfma_f32_16x16x32_bf16 v[16:19], v[182:185], v[206:209], v[16:19]
	v_mfma_f32_16x16x32_bf16 v[4:7], v[174:177], v[214:217], v[4:7]
	v_mfma_f32_16x16x32_bf16 v[0:3], v[182:185], v[214:217], v[0:3]
	s_setprio 0
	s_barrier
	s_add_i32 s80, s80, 2
	s_add_u32 s79, s79, 0x100
	s_addc_u32 vcc_hi, vcc_hi, 0
	s_cmp_gt_u32 s80, 61
	s_mov_b64 s[16:17], s[18:19]
	s_branch .LBB0_733
.LBB0_733:
	v_add_u32_e32 v155, 0x10000, v153
	ds_read_b128 v[142:145], v155
	ds_read_b128 v[156:159], v155 offset:1024
	ds_read_b128 v[160:163], v155 offset:2048
	ds_read_b128 v[166:169], v155 offset:3072
	v_add_u32_e32 v155, 0x14000, v153
	ds_read_b128 v[170:173], v155
	ds_read_b128 v[174:177], v155 offset:1024
	ds_read_b128 v[178:181], v155 offset:2048
	ds_read_b128 v[182:185], v155 offset:3072
	s_add_u32 s18, s16, 0x1000
	s_addc_u32 s19, s17, 0
	s_cmp_eq_u32 s80, 60
	s_cselect_b32 s24, vcc_lo, s18
	s_cselect_b32 s25, s11, s19
	s_cselect_b32 s22, s78, s79
	s_cselect_b32 s23, s9, vcc_hi
	s_add_u32 s20, s24, 0x800
	s_addc_u32 s21, s25, 0
	ds_read_b128 v[186:189], v154
	ds_read_b128 v[190:193], v154 offset:1024
	ds_read_b128 v[194:197], v154 offset:2048
	ds_read_b128 v[198:201], v154 offset:3072
	ds_read_b128 v[202:205], v154 offset:4096
	ds_read_b128 v[206:209], v154 offset:5120
	ds_read_b128 v[210:213], v154 offset:6144
	ds_read_b128 v[214:217], v154 offset:7168
	s_add_u32 s16, s16, 0x100800
	s_addc_u32 s17, s17, 0
	s_mov_b32 s81, m0
	s_mov_b32 m0, s83
	s_nop 0
	global_load_lds_dwordx4 v132, s[16:17]
	s_mov_b32 m0, s81
	s_add_i32 s81, s38, 0xe000
	s_mov_b32 s86, m0
	s_mov_b32 m0, s81
	s_nop 0
	global_load_lds_dwordx4 v147, s[16:17]
	s_mov_b32 m0, s86
	s_waitcnt vmcnt(8)
	s_waitcnt lgkmcnt(0)
	s_barrier
	s_setprio 1
	s_waitcnt lgkmcnt(7)
	v_mfma_f32_16x16x32_bf16 v[124:127], v[142:145], v[186:189], v[124:127]
	v_mfma_f32_16x16x32_bf16 v[120:123], v[160:163], v[186:189], v[120:123]
	s_waitcnt lgkmcnt(5)
	v_mfma_f32_16x16x32_bf16 v[108:111], v[142:145], v[194:197], v[108:111]
	v_mfma_f32_16x16x32_bf16 v[104:107], v[160:163], v[194:197], v[104:107]
	s_waitcnt lgkmcnt(3)
	v_mfma_f32_16x16x32_bf16 v[92:95], v[142:145], v[202:205], v[92:95]
	v_mfma_f32_16x16x32_bf16 v[88:91], v[160:163], v[202:205], v[88:91]
	s_waitcnt lgkmcnt(1)
	v_mfma_f32_16x16x32_bf16 v[76:79], v[142:145], v[210:213], v[76:79]
	v_mfma_f32_16x16x32_bf16 v[72:75], v[160:163], v[210:213], v[72:75]
	v_mfma_f32_16x16x32_bf16 v[124:127], v[156:159], v[190:193], v[124:127]
	v_mfma_f32_16x16x32_bf16 v[120:123], v[166:169], v[190:193], v[120:123]
	v_mfma_f32_16x16x32_bf16 v[108:111], v[156:159], v[198:201], v[108:111]
	v_mfma_f32_16x16x32_bf16 v[104:107], v[166:169], v[198:201], v[104:107]
	v_mfma_f32_16x16x32_bf16 v[92:95], v[156:159], v[206:209], v[92:95]
	v_mfma_f32_16x16x32_bf16 v[88:91], v[166:169], v[206:209], v[88:91]
	s_waitcnt lgkmcnt(0)
	v_mfma_f32_16x16x32_bf16 v[76:79], v[156:159], v[214:217], v[76:79]
	v_mfma_f32_16x16x32_bf16 v[72:75], v[166:169], v[214:217], v[72:75]
	s_setprio 0
	s_setprio 1
	v_mfma_f32_16x16x32_bf16 v[116:119], v[170:173], v[186:189], v[116:119]
	v_mfma_f32_16x16x32_bf16 v[112:115], v[178:181], v[186:189], v[112:115]
	v_mfma_f32_16x16x32_bf16 v[100:103], v[170:173], v[194:197], v[100:103]
	v_mfma_f32_16x16x32_bf16 v[96:99], v[178:181], v[194:197], v[96:99]
	v_mfma_f32_16x16x32_bf16 v[84:87], v[170:173], v[202:205], v[84:87]
	v_mfma_f32_16x16x32_bf16 v[80:83], v[178:181], v[202:205], v[80:83]
	v_mfma_f32_16x16x32_bf16 v[68:71], v[170:173], v[210:213], v[68:71]
	v_mfma_f32_16x16x32_bf16 v[64:67], v[178:181], v[210:213], v[64:67]
	v_mfma_f32_16x16x32_bf16 v[116:119], v[174:177], v[190:193], v[116:119]
	v_mfma_f32_16x16x32_bf16 v[112:115], v[182:185], v[190:193], v[112:115]
	v_mfma_f32_16x16x32_bf16 v[100:103], v[174:177], v[198:201], v[100:103]
	v_mfma_f32_16x16x32_bf16 v[96:99], v[182:185], v[198:201], v[96:99]
	v_mfma_f32_16x16x32_bf16 v[84:87], v[174:177], v[206:209], v[84:87]
	v_mfma_f32_16x16x32_bf16 v[80:83], v[182:185], v[206:209], v[80:83]
	v_mfma_f32_16x16x32_bf16 v[68:71], v[174:177], v[214:217], v[68:71]
	v_mfma_f32_16x16x32_bf16 v[64:67], v[182:185], v[214:217], v[64:67]
	s_setprio 0
	s_barrier
	ds_read_b128 v[186:189], v154 offset:16384
	ds_read_b128 v[190:193], v154 offset:17408
	ds_read_b128 v[194:197], v154 offset:18432
	ds_read_b128 v[198:201], v154 offset:19456
	ds_read_b128 v[202:205], v154 offset:20480
	ds_read_b128 v[206:209], v154 offset:21504
	ds_read_b128 v[210:213], v154 offset:22528
	ds_read_b128 v[214:217], v154 offset:23552
	s_mov_b32 s16, m0
	s_mov_b32 m0, s39
	s_nop 0
	global_load_lds_dwordx4 v146, s[22:23]
	s_mov_b32 m0, s16
	s_nop 0
	s_mov_b32 s16, m0
	s_mov_b32 m0, s40
	s_nop 0
	global_load_lds_dwordx4 v150, s[22:23]
	s_mov_b32 m0, s16
	s_add_u32 s16, s22, 0x100000
	s_addc_u32 s17, s23, 0
	s_mov_b32 s81, m0
	s_mov_b32 m0, s41
	s_nop 0
	global_load_lds_dwordx4 v146, s[16:17]
	s_mov_b32 m0, s81
	s_nop 0
	s_mov_b32 s81, m0
	s_mov_b32 m0, s65
	s_nop 0
	global_load_lds_dwordx4 v150, s[16:17]
	s_mov_b32 m0, s81
	s_mov_b32 s16, m0
	s_mov_b32 m0, s38
	s_nop 0
	global_load_lds_dwordx4 v132, s[24:25]
	s_mov_b32 m0, s16
	s_nop 0
	s_mov_b32 s16, m0
	s_mov_b32 m0, s35
	s_nop 0
	global_load_lds_dwordx4 v147, s[24:25]
	s_mov_b32 m0, s16
	s_waitcnt vmcnt(8)
	s_waitcnt lgkmcnt(0)
	s_barrier
	s_setprio 1
	s_waitcnt lgkmcnt(7)
	v_mfma_f32_16x16x32_bf16 v[60:63], v[142:145], v[186:189], v[60:63]
	v_mfma_f32_16x16x32_bf16 v[56:59], v[160:163], v[186:189], v[56:59]
	s_waitcnt lgkmcnt(5)
	v_mfma_f32_16x16x32_bf16 v[44:47], v[142:145], v[194:197], v[44:47]
	v_mfma_f32_16x16x32_bf16 v[40:43], v[160:163], v[194:197], v[40:43]
	s_waitcnt lgkmcnt(3)
	v_mfma_f32_16x16x32_bf16 v[28:31], v[142:145], v[202:205], v[28:31]
	v_mfma_f32_16x16x32_bf16 v[24:27], v[160:163], v[202:205], v[24:27]
	s_waitcnt lgkmcnt(1)
	v_mfma_f32_16x16x32_bf16 v[12:15], v[142:145], v[210:213], v[12:15]
	v_mfma_f32_16x16x32_bf16 v[8:11], v[160:163], v[210:213], v[8:11]
	v_mfma_f32_16x16x32_bf16 v[60:63], v[156:159], v[190:193], v[60:63]
	v_mfma_f32_16x16x32_bf16 v[56:59], v[166:169], v[190:193], v[56:59]
	v_mfma_f32_16x16x32_bf16 v[44:47], v[156:159], v[198:201], v[44:47]
	v_mfma_f32_16x16x32_bf16 v[40:43], v[166:169], v[198:201], v[40:43]
	v_mfma_f32_16x16x32_bf16 v[28:31], v[156:159], v[206:209], v[28:31]
	v_mfma_f32_16x16x32_bf16 v[24:27], v[166:169], v[206:209], v[24:27]
	s_waitcnt lgkmcnt(0)
	v_mfma_f32_16x16x32_bf16 v[12:15], v[156:159], v[214:217], v[12:15]
	v_mfma_f32_16x16x32_bf16 v[8:11], v[166:169], v[214:217], v[8:11]
	s_setprio 0
	s_setprio 1
	v_mfma_f32_16x16x32_bf16 v[52:55], v[170:173], v[186:189], v[52:55]
	v_mfma_f32_16x16x32_bf16 v[48:51], v[178:181], v[186:189], v[48:51]
	v_mfma_f32_16x16x32_bf16 v[36:39], v[170:173], v[194:197], v[36:39]
	v_mfma_f32_16x16x32_bf16 v[32:35], v[178:181], v[194:197], v[32:35]
	v_mfma_f32_16x16x32_bf16 v[20:23], v[170:173], v[202:205], v[20:23]
	v_mfma_f32_16x16x32_bf16 v[16:19], v[178:181], v[202:205], v[16:19]
	v_mfma_f32_16x16x32_bf16 v[4:7], v[170:173], v[210:213], v[4:7]
	v_mfma_f32_16x16x32_bf16 v[0:3], v[178:181], v[210:213], v[0:3]
	v_mfma_f32_16x16x32_bf16 v[52:55], v[174:177], v[190:193], v[52:55]
	v_mfma_f32_16x16x32_bf16 v[48:51], v[182:185], v[190:193], v[48:51]
	v_mfma_f32_16x16x32_bf16 v[36:39], v[174:177], v[198:201], v[36:39]
	v_mfma_f32_16x16x32_bf16 v[32:35], v[182:185], v[198:201], v[32:35]
	v_mfma_f32_16x16x32_bf16 v[20:23], v[174:177], v[206:209], v[20:23]
	v_mfma_f32_16x16x32_bf16 v[16:19], v[182:185], v[206:209], v[16:19]
	v_mfma_f32_16x16x32_bf16 v[4:7], v[174:177], v[214:217], v[4:7]
	v_mfma_f32_16x16x32_bf16 v[0:3], v[182:185], v[214:217], v[0:3]
	s_setprio 0
	s_barrier
	v_add_u32_e32 v155, 0x18000, v153
	ds_read_b128 v[142:145], v155
	ds_read_b128 v[156:159], v155 offset:1024
	ds_read_b128 v[160:163], v155 offset:2048
	ds_read_b128 v[166:169], v155 offset:3072
	v_add_u32_e32 v155, 0x1c000, v153
	ds_read_b128 v[170:173], v155
	ds_read_b128 v[174:177], v155 offset:1024
	ds_read_b128 v[178:181], v155 offset:2048
	ds_read_b128 v[182:185], v155 offset:3072
	ds_read_b128 v[186:189], v154 offset:32768
	ds_read_b128 v[190:193], v154 offset:33792
	ds_read_b128 v[194:197], v154 offset:34816
	ds_read_b128 v[198:201], v154 offset:35840
	ds_read_b128 v[202:205], v154 offset:36864
	ds_read_b128 v[206:209], v154 offset:37888
	ds_read_b128 v[210:213], v154 offset:38912
	ds_read_b128 v[214:217], v154 offset:39936
	s_add_u32 s16, s24, 0x100000
	s_addc_u32 s17, s25, 0
	s_mov_b32 s24, m0
	s_mov_b32 m0, s30
	s_nop 0
	global_load_lds_dwordx4 v132, s[16:17]
	s_mov_b32 m0, s24
	s_nop 0
	s_mov_b32 s24, m0
	s_mov_b32 m0, s31
	s_nop 0
	global_load_lds_dwordx4 v147, s[16:17]
	s_mov_b32 m0, s24
	s_waitcnt vmcnt(8)
	s_waitcnt lgkmcnt(0)
	s_barrier
	s_setprio 1
	s_waitcnt lgkmcnt(7)
	v_mfma_f32_16x16x32_bf16 v[124:127], v[142:145], v[186:189], v[124:127]
	v_mfma_f32_16x16x32_bf16 v[120:123], v[160:163], v[186:189], v[120:123]
	s_waitcnt lgkmcnt(5)
	v_mfma_f32_16x16x32_bf16 v[108:111], v[142:145], v[194:197], v[108:111]
	v_mfma_f32_16x16x32_bf16 v[104:107], v[160:163], v[194:197], v[104:107]
	s_waitcnt lgkmcnt(3)
	v_mfma_f32_16x16x32_bf16 v[92:95], v[142:145], v[202:205], v[92:95]
	v_mfma_f32_16x16x32_bf16 v[88:91], v[160:163], v[202:205], v[88:91]
	s_waitcnt lgkmcnt(1)
	v_mfma_f32_16x16x32_bf16 v[76:79], v[142:145], v[210:213], v[76:79]
	v_mfma_f32_16x16x32_bf16 v[72:75], v[160:163], v[210:213], v[72:75]
	v_mfma_f32_16x16x32_bf16 v[124:127], v[156:159], v[190:193], v[124:127]
	v_mfma_f32_16x16x32_bf16 v[120:123], v[166:169], v[190:193], v[120:123]
	v_mfma_f32_16x16x32_bf16 v[108:111], v[156:159], v[198:201], v[108:111]
	v_mfma_f32_16x16x32_bf16 v[104:107], v[166:169], v[198:201], v[104:107]
	v_mfma_f32_16x16x32_bf16 v[92:95], v[156:159], v[206:209], v[92:95]
	v_mfma_f32_16x16x32_bf16 v[88:91], v[166:169], v[206:209], v[88:91]
	s_waitcnt lgkmcnt(0)
	v_mfma_f32_16x16x32_bf16 v[76:79], v[156:159], v[214:217], v[76:79]
	v_mfma_f32_16x16x32_bf16 v[72:75], v[166:169], v[214:217], v[72:75]
	s_setprio 0
	s_setprio 1
	v_mfma_f32_16x16x32_bf16 v[116:119], v[170:173], v[186:189], v[116:119]
	v_mfma_f32_16x16x32_bf16 v[112:115], v[178:181], v[186:189], v[112:115]
	v_mfma_f32_16x16x32_bf16 v[100:103], v[170:173], v[194:197], v[100:103]
	v_mfma_f32_16x16x32_bf16 v[96:99], v[178:181], v[194:197], v[96:99]
	v_mfma_f32_16x16x32_bf16 v[84:87], v[170:173], v[202:205], v[84:87]
	v_mfma_f32_16x16x32_bf16 v[80:83], v[178:181], v[202:205], v[80:83]
	v_mfma_f32_16x16x32_bf16 v[68:71], v[170:173], v[210:213], v[68:71]
	v_mfma_f32_16x16x32_bf16 v[64:67], v[178:181], v[210:213], v[64:67]
	v_mfma_f32_16x16x32_bf16 v[116:119], v[174:177], v[190:193], v[116:119]
	v_mfma_f32_16x16x32_bf16 v[112:115], v[182:185], v[190:193], v[112:115]
	v_mfma_f32_16x16x32_bf16 v[100:103], v[174:177], v[198:201], v[100:103]
	v_mfma_f32_16x16x32_bf16 v[96:99], v[182:185], v[198:201], v[96:99]
	v_mfma_f32_16x16x32_bf16 v[84:87], v[174:177], v[206:209], v[84:87]
	v_mfma_f32_16x16x32_bf16 v[80:83], v[182:185], v[206:209], v[80:83]
	v_mfma_f32_16x16x32_bf16 v[68:71], v[174:177], v[214:217], v[68:71]
	v_mfma_f32_16x16x32_bf16 v[64:67], v[182:185], v[214:217], v[64:67]
	s_setprio 0
	s_barrier
	ds_read_b128 v[186:189], v154 offset:49152
	ds_read_b128 v[190:193], v154 offset:50176
	ds_read_b128 v[194:197], v154 offset:51200
	ds_read_b128 v[198:201], v154 offset:52224
	ds_read_b128 v[202:205], v154 offset:53248
	ds_read_b128 v[206:209], v154 offset:54272
	ds_read_b128 v[210:213], v154 offset:55296
	ds_read_b128 v[214:217], v154 offset:56320
	s_add_u32 s16, s22, 0x80
	s_addc_u32 s17, s23, 0
	s_mov_b32 s24, m0
	s_mov_b32 m0, s64
	s_nop 0
	global_load_lds_dwordx4 v146, s[16:17]
	s_mov_b32 m0, s24
	s_nop 0
	s_mov_b32 s24, m0
	s_mov_b32 m0, s82
	s_nop 0
	global_load_lds_dwordx4 v150, s[16:17]
	s_mov_b32 m0, s24
	s_add_u32 s16, s22, 0x100080
	s_addc_u32 s17, s23, 0
	s_mov_b32 s22, m0
	s_mov_b32 m0, s66
	s_nop 0
	global_load_lds_dwordx4 v146, s[16:17]
	s_mov_b32 m0, s22
	s_nop 0
	s_mov_b32 s22, m0
	s_mov_b32 m0, s67
	s_nop 0
	global_load_lds_dwordx4 v150, s[16:17]
	s_mov_b32 m0, s22
	s_mov_b32 s16, m0
	s_mov_b32 m0, s44
	s_nop 0
	global_load_lds_dwordx4 v132, s[20:21]
	s_mov_b32 m0, s16
	s_nop 0
	s_mov_b32 s16, m0
	s_mov_b32 m0, s45
	s_nop 0
	global_load_lds_dwordx4 v147, s[20:21]
	s_mov_b32 m0, s16
	s_waitcnt vmcnt(8)
	s_waitcnt lgkmcnt(0)
	s_barrier
	s_setprio 1
	s_waitcnt lgkmcnt(7)
	v_mfma_f32_16x16x32_bf16 v[60:63], v[142:145], v[186:189], v[60:63]
	v_mfma_f32_16x16x32_bf16 v[56:59], v[160:163], v[186:189], v[56:59]
	s_waitcnt lgkmcnt(5)
	v_mfma_f32_16x16x32_bf16 v[44:47], v[142:145], v[194:197], v[44:47]
	v_mfma_f32_16x16x32_bf16 v[40:43], v[160:163], v[194:197], v[40:43]
	s_waitcnt lgkmcnt(3)
	v_mfma_f32_16x16x32_bf16 v[28:31], v[142:145], v[202:205], v[28:31]
	v_mfma_f32_16x16x32_bf16 v[24:27], v[160:163], v[202:205], v[24:27]
	s_waitcnt lgkmcnt(1)
	v_mfma_f32_16x16x32_bf16 v[12:15], v[142:145], v[210:213], v[12:15]
	v_mfma_f32_16x16x32_bf16 v[8:11], v[160:163], v[210:213], v[8:11]
	v_mfma_f32_16x16x32_bf16 v[60:63], v[156:159], v[190:193], v[60:63]
	v_mfma_f32_16x16x32_bf16 v[56:59], v[166:169], v[190:193], v[56:59]
	v_mfma_f32_16x16x32_bf16 v[44:47], v[156:159], v[198:201], v[44:47]
	v_mfma_f32_16x16x32_bf16 v[40:43], v[166:169], v[198:201], v[40:43]
	v_mfma_f32_16x16x32_bf16 v[28:31], v[156:159], v[206:209], v[28:31]
	v_mfma_f32_16x16x32_bf16 v[24:27], v[166:169], v[206:209], v[24:27]
	s_waitcnt lgkmcnt(0)
	v_mfma_f32_16x16x32_bf16 v[12:15], v[156:159], v[214:217], v[12:15]
	v_mfma_f32_16x16x32_bf16 v[8:11], v[166:169], v[214:217], v[8:11]
	s_setprio 0
	s_setprio 1
	v_mfma_f32_16x16x32_bf16 v[52:55], v[170:173], v[186:189], v[52:55]
	v_mfma_f32_16x16x32_bf16 v[48:51], v[178:181], v[186:189], v[48:51]
	v_mfma_f32_16x16x32_bf16 v[36:39], v[170:173], v[194:197], v[36:39]
	v_mfma_f32_16x16x32_bf16 v[32:35], v[178:181], v[194:197], v[32:35]
	v_mfma_f32_16x16x32_bf16 v[20:23], v[170:173], v[202:205], v[20:23]
	v_mfma_f32_16x16x32_bf16 v[16:19], v[178:181], v[202:205], v[16:19]
	v_mfma_f32_16x16x32_bf16 v[4:7], v[170:173], v[210:213], v[4:7]
	v_mfma_f32_16x16x32_bf16 v[0:3], v[178:181], v[210:213], v[0:3]
	v_mfma_f32_16x16x32_bf16 v[52:55], v[174:177], v[190:193], v[52:55]
	v_mfma_f32_16x16x32_bf16 v[48:51], v[182:185], v[190:193], v[48:51]
	v_mfma_f32_16x16x32_bf16 v[36:39], v[174:177], v[198:201], v[36:39]
	v_mfma_f32_16x16x32_bf16 v[32:35], v[182:185], v[198:201], v[32:35]
	v_mfma_f32_16x16x32_bf16 v[20:23], v[174:177], v[206:209], v[20:23]
	v_mfma_f32_16x16x32_bf16 v[16:19], v[182:185], v[206:209], v[16:19]
	v_mfma_f32_16x16x32_bf16 v[4:7], v[174:177], v[214:217], v[4:7]
	v_mfma_f32_16x16x32_bf16 v[0:3], v[182:185], v[214:217], v[0:3]
	s_setprio 0
	s_barrier
	s_add_i32 s80, s80, 2
	s_add_u32 s79, s79, 0x100
	s_addc_u32 vcc_hi, vcc_hi, 0
	s_cmp_gt_u32 s80, 61
	s_mov_b64 s[16:17], s[18:19]
	s_cbranch_scc0 .LBB0_733
	s_and_b64 vcc, exec, s[6:7]
	s_cbranch_vccz .LBB0_736
	s_barrier
